# first K-loop iteration of the in-proj and up-proj GEMMs peeled with a literal 0 as C operand; the 128 accumulator-zeroing moves per tile removed
# baseline (speedup 1.0000x reference)
; #define PG8_STAGE(bufoff, gbase, voff) do { _Pragma("unroll") for (int _i = 0; _i < 2; ++_i) \
;         __builtin_amdgcn_global_load_lds((const unsigned*)((const char*)(gbase) + (voff)[_i]), (PG8_LAS unsigned*)(lds + (bufoff) + ldsw + _i * 8192), 16, 0, 0); } while (0)
; #define PG8_LDA(dst, b, h) do { _Pragma("unroll") for (int m = 0; m < 4; ++m) _Pragma("unroll") for (int k = 0; k < 2; ++k) dst[m][k] = *(const PG8_LAS bf16x8*)(lds + PG8_SA(b, h) + aoff + m * 2048 + k * 1024); } while (0)
; #define PG8_LDB(dst, b, h) do { _Pragma("unroll") for (int n = 0; n < 2; ++n) _Pragma("unroll") for (int k = 0; k < 2; ++k) dst[n][k] = *(const PG8_LAS bf16x8*)(lds + PG8_SB(b, h) + boff + n * 2048 + k * 1024); } while (0)
; #define PG8_BAR __builtin_amdgcn_s_barrier()
; template <class Epi, class Sched, bool ALIGN_EPI = false, bool SP2 = false, class Hook = NoHook, bool REVK = false>
; __device__ __forceinline__ void gemm_phase(PG8_LAS unsigned char* lds, const Gemm g, const Sched& S, const Epi& E, const Hook H = Hook()) {
;     ...
;         const char* nA = has_next ? (const char*)g.A + (size_t)nxt.pm * tstep + krev : cA; const char* nB = has_next ? (const char*)g.Bt + (size_t)nxt.pn * tstep + krev : cB;
;         for (int t = 0; t < nt; t += 2) {
;             if constexpr (Hook::ENABLED) H(acc, t, nt, ui, wr, fr);
;             const bool last = (t == nt - 2);
;             const char* a1 = cA + (long)(t + 1) * kstep;
;             const char* a2 = last ? nA : cA + (long)(t + 2) * kstep; const char* b2 = last ? nB : cB + (long)(t + 2) * kstep;
;             const char* a3 = a2 + kstep; const char* b3 = b2 + kstep;
;             if (last && has_next) S.a_ready(nxt);
;             if constexpr (SP2) {
;             PG8_LDB(B0, 0, 0); PG8_LDB(B1, 0, 1); PG8_SCHED; PG8_LDA(At, 0, 0); PG8_STAGE(PG8_SA(1, 1), a1 + hstep, voffA);
;             PG8_WAIT_V(8); PG8_WAIT_L(0); PG8_BAR; PG8_MMA(0, 0, At, B0); PG8_MMA(0, 1, At, B1); PG8_BAR; PG8_SCHED;
;             PG8_LDA(At, 0, 1); PG8_STAGE(PG8_SB(0, 0), b2, voffB); PG8_STAGE(PG8_SB(0, 1), b2 + hstep, voffB); PG8_STAGE(PG8_SA(0, 0), a2, voffA);
;     ...
;         for (int a = 0; a < 2; ++a)
; #pragma unroll
;             for (int b = 0; b < 2; ++b)
; #pragma unroll
;                 for (int m = 0; m < 4; ++m)
; #pragma unroll
;                     for (int n = 0; n < 2; ++n) acc[a][b][m][n] = (f32x4){0.f, 0.f, 0.f, 0.f};
.LBB0_58:
	s_ashr_i32 s93, s92, 31
	s_lshl_b64 s[22:23], s[92:93], 20
	s_add_u32 s94, s39, s22
	s_addc_u32 s95, s40, s23
	s_and_b64 s[22:23], s[6:7], exec
	s_cselect_b32 s29, s95, s27
	s_cselect_b32 s30, s94, s26
	s_ashr_i32 s91, s90, 31
	s_lshl_b64 s[22:23], s[90:91], 20
	s_add_u32 s96, s41, s22
	s_addc_u32 s97, s42, s23
	s_and_b64 s[22:23], s[6:7], exec
	s_cselect_b32 s31, s97, s21
	s_cselect_b32 s91, s96, s20
	s_add_u32 s22, s26, 0x80080
	s_addc_u32 s23, s27, 0
	s_add_u32 s93, s20, 0x100
	s_addc_u32 s98, s21, 0
	s_mov_b32 s99, -2
	s_waitcnt vmcnt(0)
	s_add_u32 s20, s22, 0xfff80080
	s_addc_u32 s21, s23, -1
	s_add_i32 s46, 0, 0x10000
	s_cmp_eq_u32 s99, 28
	s_cselect_b32 s27, s29, s21
	s_cselect_b32 s26, s30, s20
	s_cselect_b32 s21, s31, s98
	s_cselect_b32 s20, s91, s93
	s_add_i32 s58, 0, 0x14000
	v_add_u32_e32 v108, s46, v164
	v_add_u32_e32 v128, s58, v164
	ds_read_b128 v[96:99], v108
	ds_read_b128 v[100:103], v108 offset:1024
	ds_read_b128 v[104:107], v108 offset:2048
	ds_read_b128 v[108:111], v108 offset:3072
	ds_read_b128 v[182:185], v128
	ds_read_b128 v[186:189], v128 offset:1024
	ds_read_b128 v[190:193], v128 offset:2048
	ds_read_b128 v[194:197], v128 offset:3072
	v_lshl_add_u64 v[162:163], s[22:23], 0, v[158:159]
	s_add_i32 m0, s43, 0xc000
	ds_read_b128 v[200:203], v167
	ds_read_b128 v[204:207], v167 offset:1024
	ds_read_b128 v[210:213], v167 offset:2048
	ds_read_b128 v[226:229], v167 offset:3072
	ds_read_b128 v[230:233], v167 offset:4096
	ds_read_b128 v[234:237], v167 offset:5120
	ds_read_b128 v[238:241], v167 offset:6144
	ds_read_b128 v[242:245], v167 offset:7168
	global_load_lds_dwordx4 v[162:163], off
	v_lshl_add_u64 v[162:163], s[22:23], 0, v[160:161]
	s_add_i32 m0, s43, 0xe000
	s_nop 0
	global_load_lds_dwordx4 v[162:163], off
	s_waitcnt vmcnt(8)
	s_waitcnt lgkmcnt(0)
	s_setprio 1
	s_barrier
	v_mfma_f32_16x16x32_bf16 v[142:145], v[96:99], v[200:203], 0
	v_mfma_f32_16x16x32_bf16 v[138:141], v[104:107], v[200:203], 0
	v_mfma_f32_16x16x32_bf16 v[116:119], v[96:99], v[210:213], 0
	v_mfma_f32_16x16x32_bf16 v[120:123], v[104:107], v[210:213], 0
	v_mfma_f32_16x16x32_bf16 v[84:87], v[96:99], v[230:233], 0
	v_mfma_f32_16x16x32_bf16 v[88:91], v[104:107], v[230:233], 0
	v_mfma_f32_16x16x32_bf16 v[68:71], v[96:99], v[238:241], 0
	v_mfma_f32_16x16x32_bf16 v[72:75], v[104:107], v[238:241], 0
	v_mfma_f32_16x16x32_bf16 v[142:145], v[100:103], v[204:207], v[142:145]
	v_mfma_f32_16x16x32_bf16 v[138:141], v[108:111], v[204:207], v[138:141]
	v_mfma_f32_16x16x32_bf16 v[116:119], v[100:103], v[226:229], v[116:119]
	v_mfma_f32_16x16x32_bf16 v[120:123], v[108:111], v[226:229], v[120:123]
	v_mfma_f32_16x16x32_bf16 v[84:87], v[100:103], v[234:237], v[84:87]
	v_mfma_f32_16x16x32_bf16 v[88:91], v[108:111], v[234:237], v[88:91]
	v_mfma_f32_16x16x32_bf16 v[68:71], v[100:103], v[242:245], v[68:71]
	v_mfma_f32_16x16x32_bf16 v[72:75], v[108:111], v[242:245], v[72:75]
	s_setprio 0
	s_setprio 1
	v_mfma_f32_16x16x32_bf16 v[130:133], v[182:185], v[200:203], 0
	v_mfma_f32_16x16x32_bf16 v[134:137], v[190:193], v[200:203], 0
	v_mfma_f32_16x16x32_bf16 v[112:115], v[182:185], v[210:213], 0
	v_mfma_f32_16x16x32_bf16 v[124:127], v[190:193], v[210:213], 0
	v_mfma_f32_16x16x32_bf16 v[80:83], v[182:185], v[230:233], 0
	v_mfma_f32_16x16x32_bf16 v[92:95], v[190:193], v[230:233], 0
	v_mfma_f32_16x16x32_bf16 v[64:67], v[182:185], v[238:241], 0
	v_mfma_f32_16x16x32_bf16 v[76:79], v[190:193], v[238:241], 0
	v_mfma_f32_16x16x32_bf16 v[130:133], v[186:189], v[204:207], v[130:133]
	v_mfma_f32_16x16x32_bf16 v[134:137], v[194:197], v[204:207], v[134:137]
	v_mfma_f32_16x16x32_bf16 v[112:115], v[186:189], v[226:229], v[112:115]
	v_mfma_f32_16x16x32_bf16 v[124:127], v[194:197], v[226:229], v[124:127]
	v_mfma_f32_16x16x32_bf16 v[80:83], v[186:189], v[234:237], v[80:83]
	v_mfma_f32_16x16x32_bf16 v[92:95], v[194:197], v[234:237], v[92:95]
	v_mfma_f32_16x16x32_bf16 v[64:67], v[186:189], v[242:245], v[64:67]
	v_mfma_f32_16x16x32_bf16 v[76:79], v[194:197], v[242:245], v[76:79]
	s_barrier
	s_setprio 0
	s_add_i32 s46, s46, s38
	v_lshl_add_u64 v[162:163], s[20:21], 0, v[150:151]
	s_mov_b32 m0, s46
	ds_read_b128 v[200:203], v167 offset:16384
	ds_read_b128 v[204:207], v167 offset:17408
	ds_read_b128 v[210:213], v167 offset:18432
	ds_read_b128 v[226:229], v167 offset:19456
	ds_read_b128 v[230:233], v167 offset:20480
	ds_read_b128 v[234:237], v167 offset:21504
	ds_read_b128 v[238:241], v167 offset:22528
	ds_read_b128 v[242:245], v167 offset:23552
	global_load_lds_dwordx4 v[162:163], off
	s_add_i32 m0, s46, 0x2000
	s_add_u32 s56, s20, 0x80000
	v_lshl_add_u64 v[168:169], s[20:21], 0, v[146:147]
	s_addc_u32 s57, s21, 0
	s_add_i32 s46, s58, s38
	global_load_lds_dwordx4 v[168:169], off
	v_lshl_add_u64 v[214:215], s[56:57], 0, v[150:151]
	s_mov_b32 m0, s46
	v_lshl_add_u64 v[246:247], s[26:27], 0, v[148:149]
	global_load_lds_dwordx4 v[214:215], off
	v_lshl_add_u64 v[214:215], s[56:57], 0, v[146:147]
	s_add_i32 m0, s46, 0x2000
	s_nop 0
	global_load_lds_dwordx4 v[214:215], off
	v_lshl_add_u64 v[214:215], s[26:27], 0, v[152:153]
	s_mov_b32 m0, s43
	s_nop 0
	global_load_lds_dwordx4 v[214:215], off
	s_mov_b32 m0, s75
	s_nop 0
	global_load_lds_dwordx4 v[246:247], off
	s_waitcnt vmcnt(8)
	s_waitcnt lgkmcnt(0)
	s_setprio 1
	s_barrier
; #define PG8_STAGE(bufoff, gbase, voff) do { _Pragma("unroll") for (int _i = 0; _i < 2; ++_i) \
;         __builtin_amdgcn_global_load_lds((const unsigned*)((const char*)(gbase) + (voff)[_i]), (PG8_LAS unsigned*)(lds + (bufoff) + ldsw + _i * 8192), 16, 0, 0); } while (0)
; #define PG8_LDA(dst, b, h) do { _Pragma("unroll") for (int m = 0; m < 4; ++m) _Pragma("unroll") for (int k = 0; k < 2; ++k) dst[m][k] = *(const PG8_LAS bf16x8*)(lds + PG8_SA(b, h) + aoff + m * 2048 + k * 1024); } while (0)
; #define PG8_LDB(dst, b, h) do { _Pragma("unroll") for (int n = 0; n < 2; ++n) _Pragma("unroll") for (int k = 0; k < 2; ++k) dst[n][k] = *(const PG8_LAS bf16x8*)(lds + PG8_SB(b, h) + boff + n * 2048 + k * 1024); } while (0)
; #define PG8_MMA(ai, bj, At, Bt) do { __builtin_amdgcn_s_setprio(1); _Pragma("unroll") for (int m = 0; m < 4; ++m) _Pragma("unroll") for (int n = 0; n < 2; ++n) _Pragma("unroll") for (int k = 0; k < 2; ++k) \
;         acc[ai][bj][m][n] = __builtin_amdgcn_mfma_f32_16x16x32_bf16(Bt[n][k], At[m][k], acc[ai][bj][m][n], 0, 0, 0); __builtin_amdgcn_s_setprio(0); } while (0)
; #define PG8_WAIT_V(n) asm volatile("s_waitcnt vmcnt(" #n ")" ::: "memory")
; #define PG8_WAIT_L(n) asm volatile("s_waitcnt lgkmcnt(" #n ")" ::: "memory")
; #define PG8_BAR __builtin_amdgcn_s_barrier()
; template <class Epi, class Sched, bool ALIGN_EPI = false, bool SP2 = false, class Hook = NoHook, bool REVK = false>
; __device__ __forceinline__ void gemm_phase(PG8_LAS unsigned char* lds, const Gemm g, const Sched& S, const Epi& E, const Hook H = Hook()) {
;     ...
;             if constexpr (SP2) {
;             PG8_LDB(B0, 0, 0); PG8_LDB(B1, 0, 1); PG8_SCHED; PG8_LDA(At, 0, 0); PG8_STAGE(PG8_SA(1, 1), a1 + hstep, voffA);
;             PG8_WAIT_V(8); PG8_WAIT_L(0); PG8_BAR; PG8_MMA(0, 0, At, B0); PG8_MMA(0, 1, At, B1); PG8_BAR; PG8_SCHED;
;             PG8_LDA(At, 0, 1); PG8_STAGE(PG8_SB(0, 0), b2, voffB); PG8_STAGE(PG8_SB(0, 1), b2 + hstep, voffB); PG8_STAGE(PG8_SA(0, 0), a2, voffA);
;             PG8_WAIT_V(8); PG8_WAIT_L(0); PG8_BAR; PG8_MMA(1, 0, At, B0); PG8_MMA(1, 1, At, B1); PG8_BAR; PG8_SCHED;
;             PG8_LDB(B0, 1, 0); PG8_LDB(B1, 1, 1); PG8_SCHED; PG8_LDA(At, 1, 0); PG8_STAGE(PG8_SA(0, 1), a2 + hstep, voffA);
;             PG8_WAIT_V(8); PG8_WAIT_L(0); PG8_BAR; PG8_MMA(0, 0, At, B0); PG8_MMA(0, 1, At, B1); PG8_BAR; PG8_SCHED;
	v_mfma_f32_16x16x32_bf16 v[52:55], v[96:99], v[200:203], 0
	v_mfma_f32_16x16x32_bf16 v[56:59], v[104:107], v[200:203], 0
	v_mfma_f32_16x16x32_bf16 v[36:39], v[96:99], v[210:213], 0
	v_mfma_f32_16x16x32_bf16 v[40:43], v[104:107], v[210:213], 0
	v_mfma_f32_16x16x32_bf16 v[20:23], v[96:99], v[230:233], 0
	v_mfma_f32_16x16x32_bf16 v[24:27], v[104:107], v[230:233], 0
	v_mfma_f32_16x16x32_bf16 v[4:7], v[96:99], v[238:241], 0
	v_mfma_f32_16x16x32_bf16 v[8:11], v[104:107], v[238:241], 0
	v_mfma_f32_16x16x32_bf16 v[52:55], v[100:103], v[204:207], v[52:55]
	v_mfma_f32_16x16x32_bf16 v[56:59], v[108:111], v[204:207], v[56:59]
	v_mfma_f32_16x16x32_bf16 v[36:39], v[100:103], v[226:229], v[36:39]
	v_mfma_f32_16x16x32_bf16 v[40:43], v[108:111], v[226:229], v[40:43]
	v_mfma_f32_16x16x32_bf16 v[20:23], v[100:103], v[234:237], v[20:23]
	v_mfma_f32_16x16x32_bf16 v[24:27], v[108:111], v[234:237], v[24:27]
	v_mfma_f32_16x16x32_bf16 v[4:7], v[100:103], v[242:245], v[4:7]
	v_mfma_f32_16x16x32_bf16 v[8:11], v[108:111], v[242:245], v[8:11]
	s_setprio 0
	s_setprio 1
	v_mfma_f32_16x16x32_bf16 v[48:51], v[182:185], v[200:203], 0
	v_mfma_f32_16x16x32_bf16 v[60:63], v[190:193], v[200:203], 0
	v_mfma_f32_16x16x32_bf16 v[32:35], v[182:185], v[210:213], 0
	v_mfma_f32_16x16x32_bf16 v[44:47], v[190:193], v[210:213], 0
	v_mfma_f32_16x16x32_bf16 v[16:19], v[182:185], v[230:233], 0
	v_mfma_f32_16x16x32_bf16 v[28:31], v[190:193], v[230:233], 0
	v_mfma_f32_16x16x32_bf16 v[0:3], v[182:185], v[238:241], 0
	v_mfma_f32_16x16x32_bf16 v[12:15], v[190:193], v[238:241], 0
	v_mfma_f32_16x16x32_bf16 v[48:51], v[186:189], v[204:207], v[48:51]
	v_mfma_f32_16x16x32_bf16 v[60:63], v[194:197], v[204:207], v[60:63]
	v_mfma_f32_16x16x32_bf16 v[32:35], v[186:189], v[226:229], v[32:35]
	v_mfma_f32_16x16x32_bf16 v[44:47], v[194:197], v[226:229], v[44:47]
	v_mfma_f32_16x16x32_bf16 v[16:19], v[186:189], v[234:237], v[16:19]
	v_mfma_f32_16x16x32_bf16 v[28:31], v[194:197], v[234:237], v[28:31]
	v_mfma_f32_16x16x32_bf16 v[0:3], v[186:189], v[242:245], v[0:3]
	v_mfma_f32_16x16x32_bf16 v[12:15], v[194:197], v[242:245], v[12:15]
	s_barrier
	s_setprio 0
	s_add_i32 s46, 0, 0x18000
	s_add_i32 s56, 0, 0x1c000
	v_add_u32_e32 v108, s46, v164
	v_add_u32_e32 v128, s56, v164
	ds_read_b128 v[96:99], v108
	ds_read_b128 v[100:103], v108 offset:1024
	ds_read_b128 v[104:107], v108 offset:2048
	ds_read_b128 v[108:111], v108 offset:3072
	ds_read_b128 v[182:185], v128
	ds_read_b128 v[186:189], v128 offset:1024
	ds_read_b128 v[190:193], v128 offset:2048
	ds_read_b128 v[194:197], v128 offset:3072
	s_add_u32 s26, s26, 0x80000
	s_addc_u32 s27, s27, 0
	s_mov_b32 m0, s77
	v_lshl_add_u64 v[248:249], s[26:27], 0, v[152:153]
	ds_read_b128 v[200:203], v167 offset:32768
	ds_read_b128 v[204:207], v167 offset:33792
	ds_read_b128 v[210:213], v167 offset:34816
	ds_read_b128 v[226:229], v167 offset:35840
	ds_read_b128 v[230:233], v167 offset:36864
	ds_read_b128 v[234:237], v167 offset:37888
	ds_read_b128 v[238:241], v167 offset:38912
	ds_read_b128 v[242:245], v167 offset:39936
	global_load_lds_dwordx4 v[248:249], off
	v_lshl_add_u64 v[248:249], s[26:27], 0, v[148:149]
	s_mov_b32 m0, s79
	s_nop 0
	global_load_lds_dwordx4 v[248:249], off
	s_waitcnt vmcnt(8)
	s_waitcnt lgkmcnt(0)
	s_setprio 1
	s_barrier
	v_mfma_f32_16x16x32_bf16 v[142:145], v[96:99], v[200:203], v[142:145]
	v_mfma_f32_16x16x32_bf16 v[138:141], v[104:107], v[200:203], v[138:141]
	v_mfma_f32_16x16x32_bf16 v[116:119], v[96:99], v[210:213], v[116:119]
	v_mfma_f32_16x16x32_bf16 v[120:123], v[104:107], v[210:213], v[120:123]
	v_mfma_f32_16x16x32_bf16 v[84:87], v[96:99], v[230:233], v[84:87]
	v_mfma_f32_16x16x32_bf16 v[88:91], v[104:107], v[230:233], v[88:91]
	v_mfma_f32_16x16x32_bf16 v[68:71], v[96:99], v[238:241], v[68:71]
	v_mfma_f32_16x16x32_bf16 v[72:75], v[104:107], v[238:241], v[72:75]
	v_mfma_f32_16x16x32_bf16 v[142:145], v[100:103], v[204:207], v[142:145]
	v_mfma_f32_16x16x32_bf16 v[138:141], v[108:111], v[204:207], v[138:141]
	v_mfma_f32_16x16x32_bf16 v[116:119], v[100:103], v[226:229], v[116:119]
	v_mfma_f32_16x16x32_bf16 v[120:123], v[108:111], v[226:229], v[120:123]
	v_mfma_f32_16x16x32_bf16 v[84:87], v[100:103], v[234:237], v[84:87]
	v_mfma_f32_16x16x32_bf16 v[88:91], v[108:111], v[234:237], v[88:91]
	v_mfma_f32_16x16x32_bf16 v[68:71], v[100:103], v[242:245], v[68:71]
	v_mfma_f32_16x16x32_bf16 v[72:75], v[108:111], v[242:245], v[72:75]
	s_setprio 0
	s_setprio 1
	v_mfma_f32_16x16x32_bf16 v[130:133], v[182:185], v[200:203], v[130:133]
	v_mfma_f32_16x16x32_bf16 v[134:137], v[190:193], v[200:203], v[134:137]
	v_mfma_f32_16x16x32_bf16 v[112:115], v[182:185], v[210:213], v[112:115]
	v_mfma_f32_16x16x32_bf16 v[124:127], v[190:193], v[210:213], v[124:127]
	v_mfma_f32_16x16x32_bf16 v[80:83], v[182:185], v[230:233], v[80:83]
	v_mfma_f32_16x16x32_bf16 v[92:95], v[190:193], v[230:233], v[92:95]
	v_mfma_f32_16x16x32_bf16 v[64:67], v[182:185], v[238:241], v[64:67]
	v_mfma_f32_16x16x32_bf16 v[76:79], v[190:193], v[238:241], v[76:79]
	v_mfma_f32_16x16x32_bf16 v[130:133], v[186:189], v[204:207], v[130:133]
	v_mfma_f32_16x16x32_bf16 v[134:137], v[194:197], v[204:207], v[134:137]
	v_mfma_f32_16x16x32_bf16 v[112:115], v[186:189], v[226:229], v[112:115]
	v_mfma_f32_16x16x32_bf16 v[124:127], v[194:197], v[226:229], v[124:127]
	v_mfma_f32_16x16x32_bf16 v[80:83], v[186:189], v[234:237], v[80:83]
	v_mfma_f32_16x16x32_bf16 v[92:95], v[194:197], v[234:237], v[92:95]
	v_mfma_f32_16x16x32_bf16 v[64:67], v[186:189], v[242:245], v[64:67]
	v_mfma_f32_16x16x32_bf16 v[76:79], v[194:197], v[242:245], v[76:79]
	s_barrier
; #define PG8_STAGE(bufoff, gbase, voff) do { _Pragma("unroll") for (int _i = 0; _i < 2; ++_i) \
;         __builtin_amdgcn_global_load_lds((const unsigned*)((const char*)(gbase) + (voff)[_i]), (PG8_LAS unsigned*)(lds + (bufoff) + ldsw + _i * 8192), 16, 0, 0); } while (0)
; #define PG8_LDA(dst, b, h) do { _Pragma("unroll") for (int m = 0; m < 4; ++m) _Pragma("unroll") for (int k = 0; k < 2; ++k) dst[m][k] = *(const PG8_LAS bf16x8*)(lds + PG8_SA(b, h) + aoff + m * 2048 + k * 1024); } while (0)
; #define PG8_MMA(ai, bj, At, Bt) do { __builtin_amdgcn_s_setprio(1); _Pragma("unroll") for (int m = 0; m < 4; ++m) _Pragma("unroll") for (int n = 0; n < 2; ++n) _Pragma("unroll") for (int k = 0; k < 2; ++k) \
;         acc[ai][bj][m][n] = __builtin_amdgcn_mfma_f32_16x16x32_bf16(Bt[n][k], At[m][k], acc[ai][bj][m][n], 0, 0, 0); __builtin_amdgcn_s_setprio(0); } while (0)
; #define PG8_WAIT_V(n) asm volatile("s_waitcnt vmcnt(" #n ")" ::: "memory")
; #define PG8_WAIT_L(n) asm volatile("s_waitcnt lgkmcnt(" #n ")" ::: "memory")
; #define PG8_BAR __builtin_amdgcn_s_barrier()
; #define PG8_SCHED __builtin_amdgcn_sched_barrier(0)
; template <class Epi, class Sched, bool ALIGN_EPI = false, bool SP2 = false, class Hook = NoHook, bool REVK = false>
; __device__ __forceinline__ void gemm_phase(PG8_LAS unsigned char* lds, const Gemm g, const Sched& S, const Epi& E, const Hook H = Hook()) {
;     ...
;             PG8_WAIT_V(8); PG8_WAIT_L(0); PG8_BAR; PG8_MMA(0, 0, At, B0); PG8_MMA(0, 1, At, B1); PG8_BAR; PG8_SCHED;
;             PG8_LDA(At, 1, 1); PG8_STAGE(PG8_SB(1, 0), b3, voffB); PG8_STAGE(PG8_SB(1, 1), b3 + hstep, voffB); PG8_STAGE(PG8_SA(1, 0), a3, voffA);
;             PG8_WAIT_V(8); PG8_WAIT_L(0); PG8_BAR; PG8_MMA(1, 0, At, B0); PG8_MMA(1, 1, At, B1); PG8_BAR; PG8_SCHED;
	s_setprio 0
	s_add_i32 s26, s46, s38
	v_lshl_add_u64 v[162:163], v[162:163], 0, s[64:65]
	s_mov_b32 m0, s26
	ds_read_b128 v[200:203], v167 offset:49152
	ds_read_b128 v[204:207], v167 offset:50176
	ds_read_b128 v[210:213], v167 offset:51200
	ds_read_b128 v[226:229], v167 offset:52224
	ds_read_b128 v[230:233], v167 offset:53248
	ds_read_b128 v[234:237], v167 offset:54272
	ds_read_b128 v[238:241], v167 offset:55296
	ds_read_b128 v[242:245], v167 offset:56320
	global_load_lds_dwordx4 v[162:163], off
	s_add_i32 m0, s26, 0x2000
	s_add_u32 s20, s20, 0x80080
	v_lshl_add_u64 v[162:163], v[168:169], 0, s[64:65]
	s_addc_u32 s21, s21, 0
	s_add_i32 s26, s56, s38
	global_load_lds_dwordx4 v[162:163], off
	v_lshl_add_u64 v[162:163], s[20:21], 0, v[150:151]
	s_mov_b32 m0, s26
	s_nop 0
	global_load_lds_dwordx4 v[162:163], off
	v_lshl_add_u64 v[162:163], s[20:21], 0, v[146:147]
	s_add_i32 m0, s26, 0x2000
	s_nop 0
	global_load_lds_dwordx4 v[162:163], off
	v_lshl_add_u64 v[162:163], v[214:215], 0, s[64:65]
	s_mov_b32 m0, s44
	s_nop 0
	global_load_lds_dwordx4 v[162:163], off
	v_lshl_add_u64 v[162:163], v[246:247], 0, s[64:65]
	s_mov_b32 m0, s36
	s_nop 0
	global_load_lds_dwordx4 v[162:163], off
	s_waitcnt vmcnt(8)
	s_waitcnt lgkmcnt(0)
	s_setprio 1
	s_barrier
	v_mfma_f32_16x16x32_bf16 v[52:55], v[96:99], v[200:203], v[52:55]
	v_mfma_f32_16x16x32_bf16 v[56:59], v[104:107], v[200:203], v[56:59]
	v_mfma_f32_16x16x32_bf16 v[36:39], v[96:99], v[210:213], v[36:39]
	v_mfma_f32_16x16x32_bf16 v[40:43], v[104:107], v[210:213], v[40:43]
	v_mfma_f32_16x16x32_bf16 v[20:23], v[96:99], v[230:233], v[20:23]
	v_mfma_f32_16x16x32_bf16 v[24:27], v[104:107], v[230:233], v[24:27]
	v_mfma_f32_16x16x32_bf16 v[4:7], v[96:99], v[238:241], v[4:7]
	v_mfma_f32_16x16x32_bf16 v[8:11], v[104:107], v[238:241], v[8:11]
	v_mfma_f32_16x16x32_bf16 v[52:55], v[100:103], v[204:207], v[52:55]
	v_mfma_f32_16x16x32_bf16 v[56:59], v[108:111], v[204:207], v[56:59]
	v_mfma_f32_16x16x32_bf16 v[36:39], v[100:103], v[226:229], v[36:39]
	v_mfma_f32_16x16x32_bf16 v[40:43], v[108:111], v[226:229], v[40:43]
	v_mfma_f32_16x16x32_bf16 v[20:23], v[100:103], v[234:237], v[20:23]
	v_mfma_f32_16x16x32_bf16 v[24:27], v[108:111], v[234:237], v[24:27]
	v_mfma_f32_16x16x32_bf16 v[4:7], v[100:103], v[242:245], v[4:7]
	v_mfma_f32_16x16x32_bf16 v[8:11], v[108:111], v[242:245], v[8:11]
	s_setprio 0
	s_setprio 1
	v_mfma_f32_16x16x32_bf16 v[48:51], v[182:185], v[200:203], v[48:51]
	v_mfma_f32_16x16x32_bf16 v[60:63], v[190:193], v[200:203], v[60:63]
	v_mfma_f32_16x16x32_bf16 v[32:35], v[182:185], v[210:213], v[32:35]
	v_mfma_f32_16x16x32_bf16 v[44:47], v[190:193], v[210:213], v[44:47]
	v_mfma_f32_16x16x32_bf16 v[16:19], v[182:185], v[230:233], v[16:19]
	v_mfma_f32_16x16x32_bf16 v[28:31], v[190:193], v[230:233], v[28:31]
	v_mfma_f32_16x16x32_bf16 v[0:3], v[182:185], v[238:241], v[0:3]
	v_mfma_f32_16x16x32_bf16 v[12:15], v[190:193], v[238:241], v[12:15]
	v_mfma_f32_16x16x32_bf16 v[48:51], v[186:189], v[204:207], v[48:51]
	v_mfma_f32_16x16x32_bf16 v[60:63], v[194:197], v[204:207], v[60:63]
	v_mfma_f32_16x16x32_bf16 v[32:35], v[186:189], v[226:229], v[32:35]
	v_mfma_f32_16x16x32_bf16 v[44:47], v[194:197], v[226:229], v[44:47]
	v_mfma_f32_16x16x32_bf16 v[16:19], v[186:189], v[234:237], v[16:19]
	v_mfma_f32_16x16x32_bf16 v[28:31], v[194:197], v[234:237], v[28:31]
	v_mfma_f32_16x16x32_bf16 v[0:3], v[186:189], v[242:245], v[0:3]
	v_mfma_f32_16x16x32_bf16 v[12:15], v[194:197], v[242:245], v[12:15]
	s_barrier
	s_setprio 0
	s_add_i32 s99, s99, 2
	s_add_u32 s22, s22, 0x100
	s_addc_u32 s23, s23, 0
	s_add_u32 s93, s93, 0x100
	s_addc_u32 s98, s98, 0
	s_cmp_gt_u32 s99, 29

; #define PG8_STAGE(bufoff, gbase, voff) do { _Pragma("unroll") for (int _i = 0; _i < 2; ++_i) \
;         __builtin_amdgcn_global_load_lds((const unsigned*)((const char*)(gbase) + (voff)[_i]), (PG8_LAS unsigned*)(lds + (bufoff) + ldsw + _i * 8192), 16, 0, 0); } while (0)
; #define PG8_LDA(dst, b, h) do { _Pragma("unroll") for (int m = 0; m < 4; ++m) _Pragma("unroll") for (int k = 0; k < 2; ++k) dst[m][k] = *(const PG8_LAS bf16x8*)(lds + PG8_SA(b, h) + aoff + m * 2048 + k * 1024); } while (0)
; #define PG8_LDB(dst, b, h) do { _Pragma("unroll") for (int n = 0; n < 2; ++n) _Pragma("unroll") for (int k = 0; k < 2; ++k) dst[n][k] = *(const PG8_LAS bf16x8*)(lds + PG8_SB(b, h) + boff + n * 2048 + k * 1024); } while (0)
; #define PG8_WAIT_V(n) asm volatile("s_waitcnt vmcnt(" #n ")" ::: "memory")
; #define PG8_WAIT_L(n) asm volatile("s_waitcnt lgkmcnt(" #n ")" ::: "memory")
; template <class Epi, class Sched, bool ALIGN_EPI = false, bool SP2 = false, class Hook = NoHook, bool REVK = false>
; __device__ __forceinline__ void gemm_phase(PG8_LAS unsigned char* lds, const Gemm g, const Sched& S, const Epi& E, const Hook H = Hook()) {
;     ...
;         const bool has_next = S.next(ui + 1, nxt);
;         const char* nA = has_next ? (const char*)g.A + (size_t)nxt.pm * tstep + krev : cA; const char* nB = has_next ? (const char*)g.Bt + (size_t)nxt.pn * tstep + krev : cB;
;         for (int t = 0; t < nt; t += 2) {
;             if constexpr (Hook::ENABLED) H(acc, t, nt, ui, wr, fr);
;             const bool last = (t == nt - 2);
;             const char* a1 = cA + (long)(t + 1) * kstep;
;             const char* a2 = last ? nA : cA + (long)(t + 2) * kstep; const char* b2 = last ? nB : cB + (long)(t + 2) * kstep;
;             const char* a3 = a2 + kstep; const char* b3 = b2 + kstep;
;             if (last && has_next) S.a_ready(nxt);
;             if constexpr (SP2) {
;             PG8_LDB(B0, 0, 0); PG8_LDB(B1, 0, 1); PG8_SCHED; PG8_LDA(At, 0, 0); PG8_STAGE(PG8_SA(1, 1), a1 + hstep, voffA);
;             PG8_WAIT_V(8); PG8_WAIT_L(0); PG8_BAR; PG8_MMA(0, 0, At, B0); PG8_MMA(0, 1, At, B1); PG8_BAR; PG8_SCHED;
;             PG8_LDA(At, 0, 1); PG8_STAGE(PG8_SB(0, 0), b2, voffB); PG8_STAGE(PG8_SB(0, 1), b2 + hstep, voffB); PG8_STAGE(PG8_SA(0, 0), a2, voffA);
;             PG8_WAIT_V(8); PG8_WAIT_L(0); PG8_BAR; PG8_MMA(1, 0, At, B0); PG8_MMA(1, 1, At, B1); PG8_BAR; PG8_SCHED;
.LBB0_581:
	s_ashr_i32 s87, s86, 31
	s_lshl_b64 s[26:27], s[86:87], 20
	s_add_u32 s88, s11, s26
	s_addc_u32 s89, s24, s27
	s_and_b64 s[26:27], s[6:7], exec
	s_cselect_b32 s41, s89, s23
	s_cselect_b32 s42, s88, s22
	s_ashr_i32 s85, s84, 31
	s_lshl_b64 s[26:27], s[84:85], 20
	s_add_u32 s90, s28, s26
	s_addc_u32 s91, s29, s27
	s_and_b64 s[26:27], s[6:7], exec
	s_cselect_b32 s43, s91, s21
	s_cselect_b32 s44, s90, s20
	s_add_u32 s22, s22, 0x80080
	s_addc_u32 s23, s23, 0
	s_add_u32 s47, s20, 0x100
	s_addc_u32 s51, s21, 0
	s_mov_b32 s53, -2
	s_add_u32 s20, s22, 0xfff80080
	s_addc_u32 s21, s23, -1
	s_add_i32 s46, 0, 0x10000
	s_cmp_eq_u32 s53, 28
	s_cselect_b32 s27, s41, s21
	s_cselect_b32 s26, s42, s20
	v_add_u32_e32 v144, s46, v147
	s_cselect_b32 s21, s43, s51
	s_cselect_b32 s20, s44, s47
	s_add_i32 s58, 0, 0x14000
	ds_read_b128 v[140:143], v144
	ds_read_b128 v[152:155], v144 offset:1024
	ds_read_b128 v[156:159], v144 offset:2048
	ds_read_b128 v[160:163], v144 offset:3072
	v_add_u32_e32 v144, s58, v147
	ds_read_b128 v[164:167], v144
	ds_read_b128 v[182:185], v144 offset:1024
	ds_read_b128 v[186:189], v144 offset:2048
	ds_read_b128 v[190:193], v144 offset:3072
	v_lshl_add_u64 v[144:145], s[22:23], 0, v[136:137]
	s_add_i32 m0, s30, 0xc000
	ds_read_b128 v[194:197], v150
	ds_read_b128 v[200:203], v150 offset:1024
	ds_read_b128 v[204:207], v150 offset:2048
	ds_read_b128 v[210:213], v150 offset:3072
	ds_read_b128 v[226:229], v150 offset:4096
	ds_read_b128 v[230:233], v150 offset:5120
	ds_read_b128 v[234:237], v150 offset:6144
	ds_read_b128 v[238:241], v150 offset:7168
	global_load_lds_dwordx4 v[144:145], off
	v_lshl_add_u64 v[144:145], s[22:23], 0, v[138:139]
	s_add_i32 m0, s30, 0xe000
	s_nop 0
	global_load_lds_dwordx4 v[144:145], off
	s_waitcnt vmcnt(8)
	s_waitcnt lgkmcnt(0)
	s_setprio 1
	s_barrier
	v_mfma_f32_16x16x32_bf16 v[124:127], v[140:143], v[194:197], 0
	v_mfma_f32_16x16x32_bf16 v[120:123], v[156:159], v[194:197], 0
	v_mfma_f32_16x16x32_bf16 v[108:111], v[140:143], v[204:207], 0
	v_mfma_f32_16x16x32_bf16 v[104:107], v[156:159], v[204:207], 0
	v_mfma_f32_16x16x32_bf16 v[92:95], v[140:143], v[226:229], 0
	v_mfma_f32_16x16x32_bf16 v[88:91], v[156:159], v[226:229], 0
	v_mfma_f32_16x16x32_bf16 v[76:79], v[140:143], v[234:237], 0
	v_mfma_f32_16x16x32_bf16 v[72:75], v[156:159], v[234:237], 0
	v_mfma_f32_16x16x32_bf16 v[124:127], v[152:155], v[200:203], v[124:127]
	v_mfma_f32_16x16x32_bf16 v[120:123], v[160:163], v[200:203], v[120:123]
	v_mfma_f32_16x16x32_bf16 v[108:111], v[152:155], v[210:213], v[108:111]
	v_mfma_f32_16x16x32_bf16 v[104:107], v[160:163], v[210:213], v[104:107]
	v_mfma_f32_16x16x32_bf16 v[92:95], v[152:155], v[230:233], v[92:95]
	v_mfma_f32_16x16x32_bf16 v[88:91], v[160:163], v[230:233], v[88:91]
	v_mfma_f32_16x16x32_bf16 v[76:79], v[152:155], v[238:241], v[76:79]
	v_mfma_f32_16x16x32_bf16 v[72:75], v[160:163], v[238:241], v[72:75]
	s_setprio 0
	s_setprio 1
	v_mfma_f32_16x16x32_bf16 v[116:119], v[164:167], v[194:197], 0
	v_mfma_f32_16x16x32_bf16 v[112:115], v[186:189], v[194:197], 0
	v_mfma_f32_16x16x32_bf16 v[100:103], v[164:167], v[204:207], 0
	v_mfma_f32_16x16x32_bf16 v[96:99], v[186:189], v[204:207], 0
	v_mfma_f32_16x16x32_bf16 v[84:87], v[164:167], v[226:229], 0
	v_mfma_f32_16x16x32_bf16 v[80:83], v[186:189], v[226:229], 0
	v_mfma_f32_16x16x32_bf16 v[68:71], v[164:167], v[234:237], 0
	v_mfma_f32_16x16x32_bf16 v[64:67], v[186:189], v[234:237], 0
	v_mfma_f32_16x16x32_bf16 v[116:119], v[182:185], v[200:203], v[116:119]
	v_mfma_f32_16x16x32_bf16 v[112:115], v[190:193], v[200:203], v[112:115]
	v_mfma_f32_16x16x32_bf16 v[100:103], v[182:185], v[210:213], v[100:103]
	v_mfma_f32_16x16x32_bf16 v[96:99], v[190:193], v[210:213], v[96:99]
	v_mfma_f32_16x16x32_bf16 v[84:87], v[182:185], v[230:233], v[84:87]
	v_mfma_f32_16x16x32_bf16 v[80:83], v[190:193], v[230:233], v[80:83]
	v_mfma_f32_16x16x32_bf16 v[68:71], v[182:185], v[238:241], v[68:71]
	v_mfma_f32_16x16x32_bf16 v[64:67], v[190:193], v[238:241], v[64:67]
	s_barrier
	s_setprio 0
	s_add_i32 s46, s46, s10
	v_lshl_add_u64 v[144:145], s[20:21], 0, v[128:129]
	s_mov_b32 m0, s46
	ds_read_b128 v[194:197], v150 offset:16384
	ds_read_b128 v[200:203], v150 offset:17408
	ds_read_b128 v[204:207], v150 offset:18432
	ds_read_b128 v[210:213], v150 offset:19456
	ds_read_b128 v[226:229], v150 offset:20480
	ds_read_b128 v[230:233], v150 offset:21504
	ds_read_b128 v[234:237], v150 offset:22528
	ds_read_b128 v[238:241], v150 offset:23552
	global_load_lds_dwordx4 v[144:145], off
	s_add_i32 m0, s46, 0x2000
	s_add_u32 s56, s20, 0x80000
	v_lshl_add_u64 v[168:169], s[20:21], 0, v[130:131]
	s_addc_u32 s57, s21, 0
	s_add_i32 s46, s58, s10
	global_load_lds_dwordx4 v[168:169], off
	v_lshl_add_u64 v[214:215], s[56:57], 0, v[128:129]
	s_mov_b32 m0, s46
	v_lshl_add_u64 v[242:243], s[26:27], 0, v[132:133]
	global_load_lds_dwordx4 v[214:215], off
	v_lshl_add_u64 v[214:215], s[56:57], 0, v[130:131]
	s_add_i32 m0, s46, 0x2000
	s_nop 0
	global_load_lds_dwordx4 v[214:215], off
	v_lshl_add_u64 v[214:215], s[26:27], 0, v[134:135]
	s_mov_b32 m0, s30
	s_nop 0
	global_load_lds_dwordx4 v[214:215], off
	s_mov_b32 m0, s31
	s_nop 0
	global_load_lds_dwordx4 v[242:243], off
	s_waitcnt vmcnt(8)
	s_waitcnt lgkmcnt(0)
	s_setprio 1
	s_barrier
; #define PG8_STAGE(bufoff, gbase, voff) do { _Pragma("unroll") for (int _i = 0; _i < 2; ++_i) \
;         __builtin_amdgcn_global_load_lds((const unsigned*)((const char*)(gbase) + (voff)[_i]), (PG8_LAS unsigned*)(lds + (bufoff) + ldsw + _i * 8192), 16, 0, 0); } while (0)
; #define PG8_LDA(dst, b, h) do { _Pragma("unroll") for (int m = 0; m < 4; ++m) _Pragma("unroll") for (int k = 0; k < 2; ++k) dst[m][k] = *(const PG8_LAS bf16x8*)(lds + PG8_SA(b, h) + aoff + m * 2048 + k * 1024); } while (0)
; #define PG8_LDB(dst, b, h) do { _Pragma("unroll") for (int n = 0; n < 2; ++n) _Pragma("unroll") for (int k = 0; k < 2; ++k) dst[n][k] = *(const PG8_LAS bf16x8*)(lds + PG8_SB(b, h) + boff + n * 2048 + k * 1024); } while (0)
; #define PG8_MMA(ai, bj, At, Bt) do { __builtin_amdgcn_s_setprio(1); _Pragma("unroll") for (int m = 0; m < 4; ++m) _Pragma("unroll") for (int n = 0; n < 2; ++n) _Pragma("unroll") for (int k = 0; k < 2; ++k) \
;         acc[ai][bj][m][n] = __builtin_amdgcn_mfma_f32_16x16x32_bf16(Bt[n][k], At[m][k], acc[ai][bj][m][n], 0, 0, 0); __builtin_amdgcn_s_setprio(0); } while (0)
; #define PG8_WAIT_V(n) asm volatile("s_waitcnt vmcnt(" #n ")" ::: "memory")
; #define PG8_WAIT_L(n) asm volatile("s_waitcnt lgkmcnt(" #n ")" ::: "memory")
; #define PG8_BAR __builtin_amdgcn_s_barrier()
; #define PG8_SCHED __builtin_amdgcn_sched_barrier(0)
; template <class Epi, class Sched, bool ALIGN_EPI = false, bool SP2 = false, class Hook = NoHook, bool REVK = false>
; __device__ __forceinline__ void gemm_phase(PG8_LAS unsigned char* lds, const Gemm g, const Sched& S, const Epi& E, const Hook H = Hook()) {
;     ...
;             PG8_WAIT_V(8); PG8_WAIT_L(0); PG8_BAR; PG8_MMA(1, 0, At, B0); PG8_MMA(1, 1, At, B1); PG8_BAR; PG8_SCHED;
;             PG8_LDB(B0, 1, 0); PG8_LDB(B1, 1, 1); PG8_SCHED; PG8_LDA(At, 1, 0); PG8_STAGE(PG8_SA(0, 1), a2 + hstep, voffA);
;             PG8_WAIT_V(8); PG8_WAIT_L(0); PG8_BAR; PG8_MMA(0, 0, At, B0); PG8_MMA(0, 1, At, B1); PG8_BAR; PG8_SCHED;
	v_mfma_f32_16x16x32_bf16 v[60:63], v[140:143], v[194:197], 0
	v_mfma_f32_16x16x32_bf16 v[56:59], v[156:159], v[194:197], 0
	v_mfma_f32_16x16x32_bf16 v[44:47], v[140:143], v[204:207], 0
	v_mfma_f32_16x16x32_bf16 v[40:43], v[156:159], v[204:207], 0
	v_mfma_f32_16x16x32_bf16 v[28:31], v[140:143], v[226:229], 0
	v_mfma_f32_16x16x32_bf16 v[24:27], v[156:159], v[226:229], 0
	v_mfma_f32_16x16x32_bf16 v[12:15], v[140:143], v[234:237], 0
	v_mfma_f32_16x16x32_bf16 v[8:11], v[156:159], v[234:237], 0
	v_mfma_f32_16x16x32_bf16 v[60:63], v[152:155], v[200:203], v[60:63]
	v_mfma_f32_16x16x32_bf16 v[56:59], v[160:163], v[200:203], v[56:59]
	v_mfma_f32_16x16x32_bf16 v[44:47], v[152:155], v[210:213], v[44:47]
	v_mfma_f32_16x16x32_bf16 v[40:43], v[160:163], v[210:213], v[40:43]
	v_mfma_f32_16x16x32_bf16 v[28:31], v[152:155], v[230:233], v[28:31]
	v_mfma_f32_16x16x32_bf16 v[24:27], v[160:163], v[230:233], v[24:27]
	v_mfma_f32_16x16x32_bf16 v[12:15], v[152:155], v[238:241], v[12:15]
	v_mfma_f32_16x16x32_bf16 v[8:11], v[160:163], v[238:241], v[8:11]
	s_setprio 0
	s_setprio 1
	v_mfma_f32_16x16x32_bf16 v[52:55], v[164:167], v[194:197], 0
	v_mfma_f32_16x16x32_bf16 v[48:51], v[186:189], v[194:197], 0
	v_mfma_f32_16x16x32_bf16 v[36:39], v[164:167], v[204:207], 0
	v_mfma_f32_16x16x32_bf16 v[32:35], v[186:189], v[204:207], 0
	v_mfma_f32_16x16x32_bf16 v[20:23], v[164:167], v[226:229], 0
	v_mfma_f32_16x16x32_bf16 v[16:19], v[186:189], v[226:229], 0
	v_mfma_f32_16x16x32_bf16 v[4:7], v[164:167], v[234:237], 0
	v_mfma_f32_16x16x32_bf16 v[0:3], v[186:189], v[234:237], 0
	v_mfma_f32_16x16x32_bf16 v[52:55], v[182:185], v[200:203], v[52:55]
	v_mfma_f32_16x16x32_bf16 v[48:51], v[190:193], v[200:203], v[48:51]
	v_mfma_f32_16x16x32_bf16 v[36:39], v[182:185], v[210:213], v[36:39]
	v_mfma_f32_16x16x32_bf16 v[32:35], v[190:193], v[210:213], v[32:35]
	v_mfma_f32_16x16x32_bf16 v[20:23], v[182:185], v[230:233], v[20:23]
	v_mfma_f32_16x16x32_bf16 v[16:19], v[190:193], v[230:233], v[16:19]
	v_mfma_f32_16x16x32_bf16 v[4:7], v[182:185], v[238:241], v[4:7]
	v_mfma_f32_16x16x32_bf16 v[0:3], v[190:193], v[238:241], v[0:3]
	s_barrier
	s_setprio 0
	s_add_i32 s46, 0, 0x18000
	v_add_u32_e32 v151, s46, v147
	s_add_i32 s56, 0, 0x1c000
	ds_read_b128 v[140:143], v151
	ds_read_b128 v[152:155], v151 offset:1024
	ds_read_b128 v[156:159], v151 offset:2048
	ds_read_b128 v[160:163], v151 offset:3072
	v_add_u32_e32 v151, s56, v147
	ds_read_b128 v[164:167], v151
	ds_read_b128 v[182:185], v151 offset:1024
	ds_read_b128 v[186:189], v151 offset:2048
	ds_read_b128 v[190:193], v151 offset:3072
	s_add_u32 s26, s26, 0x80000
	s_addc_u32 s27, s27, 0
	s_mov_b32 m0, s34
	v_lshl_add_u64 v[244:245], s[26:27], 0, v[134:135]
	ds_read_b128 v[194:197], v150 offset:32768
	ds_read_b128 v[200:203], v150 offset:33792
	ds_read_b128 v[204:207], v150 offset:34816
	ds_read_b128 v[210:213], v150 offset:35840
	ds_read_b128 v[226:229], v150 offset:36864
	ds_read_b128 v[230:233], v150 offset:37888
	ds_read_b128 v[234:237], v150 offset:38912
	ds_read_b128 v[238:241], v150 offset:39936
	global_load_lds_dwordx4 v[244:245], off
	v_lshl_add_u64 v[244:245], s[26:27], 0, v[132:133]
	s_mov_b32 m0, s35
	s_nop 0
	global_load_lds_dwordx4 v[244:245], off
	s_waitcnt vmcnt(8)
	s_waitcnt lgkmcnt(0)
	s_setprio 1
	s_barrier
	v_mfma_f32_16x16x32_bf16 v[124:127], v[140:143], v[194:197], v[124:127]
	v_mfma_f32_16x16x32_bf16 v[120:123], v[156:159], v[194:197], v[120:123]
	v_mfma_f32_16x16x32_bf16 v[108:111], v[140:143], v[204:207], v[108:111]
	v_mfma_f32_16x16x32_bf16 v[104:107], v[156:159], v[204:207], v[104:107]
	v_mfma_f32_16x16x32_bf16 v[92:95], v[140:143], v[226:229], v[92:95]
	v_mfma_f32_16x16x32_bf16 v[88:91], v[156:159], v[226:229], v[88:91]
	v_mfma_f32_16x16x32_bf16 v[76:79], v[140:143], v[234:237], v[76:79]
	v_mfma_f32_16x16x32_bf16 v[72:75], v[156:159], v[234:237], v[72:75]
	v_mfma_f32_16x16x32_bf16 v[124:127], v[152:155], v[200:203], v[124:127]
	v_mfma_f32_16x16x32_bf16 v[120:123], v[160:163], v[200:203], v[120:123]
	v_mfma_f32_16x16x32_bf16 v[108:111], v[152:155], v[210:213], v[108:111]
	v_mfma_f32_16x16x32_bf16 v[104:107], v[160:163], v[210:213], v[104:107]
	v_mfma_f32_16x16x32_bf16 v[92:95], v[152:155], v[230:233], v[92:95]
	v_mfma_f32_16x16x32_bf16 v[88:91], v[160:163], v[230:233], v[88:91]
	v_mfma_f32_16x16x32_bf16 v[76:79], v[152:155], v[238:241], v[76:79]
	v_mfma_f32_16x16x32_bf16 v[72:75], v[160:163], v[238:241], v[72:75]
	s_setprio 0
	s_setprio 1
	v_mfma_f32_16x16x32_bf16 v[116:119], v[164:167], v[194:197], v[116:119]
	v_mfma_f32_16x16x32_bf16 v[112:115], v[186:189], v[194:197], v[112:115]
	v_mfma_f32_16x16x32_bf16 v[100:103], v[164:167], v[204:207], v[100:103]
	v_mfma_f32_16x16x32_bf16 v[96:99], v[186:189], v[204:207], v[96:99]
	v_mfma_f32_16x16x32_bf16 v[84:87], v[164:167], v[226:229], v[84:87]
	v_mfma_f32_16x16x32_bf16 v[80:83], v[186:189], v[226:229], v[80:83]
	v_mfma_f32_16x16x32_bf16 v[68:71], v[164:167], v[234:237], v[68:71]
	v_mfma_f32_16x16x32_bf16 v[64:67], v[186:189], v[234:237], v[64:67]
	v_mfma_f32_16x16x32_bf16 v[116:119], v[182:185], v[200:203], v[116:119]
	v_mfma_f32_16x16x32_bf16 v[112:115], v[190:193], v[200:203], v[112:115]
	v_mfma_f32_16x16x32_bf16 v[100:103], v[182:185], v[210:213], v[100:103]
	v_mfma_f32_16x16x32_bf16 v[96:99], v[190:193], v[210:213], v[96:99]
	v_mfma_f32_16x16x32_bf16 v[84:87], v[182:185], v[230:233], v[84:87]
	v_mfma_f32_16x16x32_bf16 v[80:83], v[190:193], v[230:233], v[80:83]
	v_mfma_f32_16x16x32_bf16 v[68:71], v[182:185], v[238:241], v[68:71]
	v_mfma_f32_16x16x32_bf16 v[64:67], v[190:193], v[238:241], v[64:67]
	s_barrier
; #define PG8_STAGE(bufoff, gbase, voff) do { _Pragma("unroll") for (int _i = 0; _i < 2; ++_i) \
;         __builtin_amdgcn_global_load_lds((const unsigned*)((const char*)(gbase) + (voff)[_i]), (PG8_LAS unsigned*)(lds + (bufoff) + ldsw + _i * 8192), 16, 0, 0); } while (0)
; #define PG8_LDA(dst, b, h) do { _Pragma("unroll") for (int m = 0; m < 4; ++m) _Pragma("unroll") for (int k = 0; k < 2; ++k) dst[m][k] = *(const PG8_LAS bf16x8*)(lds + PG8_SA(b, h) + aoff + m * 2048 + k * 1024); } while (0)
; #define PG8_MMA(ai, bj, At, Bt) do { __builtin_amdgcn_s_setprio(1); _Pragma("unroll") for (int m = 0; m < 4; ++m) _Pragma("unroll") for (int n = 0; n < 2; ++n) _Pragma("unroll") for (int k = 0; k < 2; ++k) \
;         acc[ai][bj][m][n] = __builtin_amdgcn_mfma_f32_16x16x32_bf16(Bt[n][k], At[m][k], acc[ai][bj][m][n], 0, 0, 0); __builtin_amdgcn_s_setprio(0); } while (0)
; #define PG8_WAIT_V(n) asm volatile("s_waitcnt vmcnt(" #n ")" ::: "memory")
; #define PG8_WAIT_L(n) asm volatile("s_waitcnt lgkmcnt(" #n ")" ::: "memory")
; #define PG8_BAR __builtin_amdgcn_s_barrier()
; #define PG8_SCHED __builtin_amdgcn_sched_barrier(0)
; template <class Epi, class Sched, bool ALIGN_EPI = false, bool SP2 = false, class Hook = NoHook, bool REVK = false>
; __device__ __forceinline__ void gemm_phase(PG8_LAS unsigned char* lds, const Gemm g, const Sched& S, const Epi& E, const Hook H = Hook()) {
;     ...
;         for (int t = 0; t < nt; t += 2) {
;     ...
;             PG8_LDA(At, 1, 1); PG8_STAGE(PG8_SB(1, 0), b3, voffB); PG8_STAGE(PG8_SB(1, 1), b3 + hstep, voffB); PG8_STAGE(PG8_SA(1, 0), a3, voffA);
;             PG8_WAIT_V(8); PG8_WAIT_L(0); PG8_BAR; PG8_MMA(1, 0, At, B0); PG8_MMA(1, 1, At, B1); PG8_BAR; PG8_SCHED;
	s_setprio 0
	s_add_i32 s26, s46, s10
	v_lshl_add_u64 v[144:145], v[144:145], 0, s[64:65]
	s_mov_b32 m0, s26
	ds_read_b128 v[194:197], v150 offset:49152
	ds_read_b128 v[200:203], v150 offset:50176
	ds_read_b128 v[204:207], v150 offset:51200
	ds_read_b128 v[210:213], v150 offset:52224
	ds_read_b128 v[226:229], v150 offset:53248
	ds_read_b128 v[230:233], v150 offset:54272
	ds_read_b128 v[234:237], v150 offset:55296
	ds_read_b128 v[238:241], v150 offset:56320
	global_load_lds_dwordx4 v[144:145], off
	s_add_i32 m0, s26, 0x2000
	s_add_u32 s20, s20, 0x80080
	v_lshl_add_u64 v[144:145], v[168:169], 0, s[64:65]
	s_addc_u32 s21, s21, 0
	s_add_i32 s26, s56, s10
	global_load_lds_dwordx4 v[144:145], off
	v_lshl_add_u64 v[144:145], s[20:21], 0, v[128:129]
	s_mov_b32 m0, s26
	s_nop 0
	global_load_lds_dwordx4 v[144:145], off
	v_lshl_add_u64 v[144:145], s[20:21], 0, v[130:131]
	s_add_i32 m0, s26, 0x2000
	s_nop 0
	global_load_lds_dwordx4 v[144:145], off
	v_lshl_add_u64 v[144:145], v[214:215], 0, s[64:65]
	s_mov_b32 m0, s36
	s_nop 0
	global_load_lds_dwordx4 v[144:145], off
	v_lshl_add_u64 v[144:145], v[242:243], 0, s[64:65]
	s_mov_b32 m0, s38
	s_nop 0
	global_load_lds_dwordx4 v[144:145], off
	s_waitcnt vmcnt(8)
	s_waitcnt lgkmcnt(0)
	s_setprio 1
	s_barrier
	v_mfma_f32_16x16x32_bf16 v[60:63], v[140:143], v[194:197], v[60:63]
	v_mfma_f32_16x16x32_bf16 v[56:59], v[156:159], v[194:197], v[56:59]
	v_mfma_f32_16x16x32_bf16 v[44:47], v[140:143], v[204:207], v[44:47]
	v_mfma_f32_16x16x32_bf16 v[40:43], v[156:159], v[204:207], v[40:43]
	v_mfma_f32_16x16x32_bf16 v[28:31], v[140:143], v[226:229], v[28:31]
	v_mfma_f32_16x16x32_bf16 v[24:27], v[156:159], v[226:229], v[24:27]
	v_mfma_f32_16x16x32_bf16 v[12:15], v[140:143], v[234:237], v[12:15]
	v_mfma_f32_16x16x32_bf16 v[8:11], v[156:159], v[234:237], v[8:11]
	v_mfma_f32_16x16x32_bf16 v[60:63], v[152:155], v[200:203], v[60:63]
	v_mfma_f32_16x16x32_bf16 v[56:59], v[160:163], v[200:203], v[56:59]
	v_mfma_f32_16x16x32_bf16 v[44:47], v[152:155], v[210:213], v[44:47]
	v_mfma_f32_16x16x32_bf16 v[40:43], v[160:163], v[210:213], v[40:43]
	v_mfma_f32_16x16x32_bf16 v[28:31], v[152:155], v[230:233], v[28:31]
	v_mfma_f32_16x16x32_bf16 v[24:27], v[160:163], v[230:233], v[24:27]
	v_mfma_f32_16x16x32_bf16 v[12:15], v[152:155], v[238:241], v[12:15]
	v_mfma_f32_16x16x32_bf16 v[8:11], v[160:163], v[238:241], v[8:11]
	s_setprio 0
	s_setprio 1
	v_mfma_f32_16x16x32_bf16 v[52:55], v[164:167], v[194:197], v[52:55]
	v_mfma_f32_16x16x32_bf16 v[48:51], v[186:189], v[194:197], v[48:51]
	v_mfma_f32_16x16x32_bf16 v[36:39], v[164:167], v[204:207], v[36:39]
	v_mfma_f32_16x16x32_bf16 v[32:35], v[186:189], v[204:207], v[32:35]
	v_mfma_f32_16x16x32_bf16 v[20:23], v[164:167], v[226:229], v[20:23]
	v_mfma_f32_16x16x32_bf16 v[16:19], v[186:189], v[226:229], v[16:19]
	v_mfma_f32_16x16x32_bf16 v[4:7], v[164:167], v[234:237], v[4:7]
	v_mfma_f32_16x16x32_bf16 v[0:3], v[186:189], v[234:237], v[0:3]
	v_mfma_f32_16x16x32_bf16 v[52:55], v[182:185], v[200:203], v[52:55]
	v_mfma_f32_16x16x32_bf16 v[48:51], v[190:193], v[200:203], v[48:51]
	v_mfma_f32_16x16x32_bf16 v[36:39], v[182:185], v[210:213], v[36:39]
	v_mfma_f32_16x16x32_bf16 v[32:35], v[190:193], v[210:213], v[32:35]
	v_mfma_f32_16x16x32_bf16 v[20:23], v[182:185], v[230:233], v[20:23]
	v_mfma_f32_16x16x32_bf16 v[16:19], v[190:193], v[230:233], v[16:19]
	v_mfma_f32_16x16x32_bf16 v[4:7], v[182:185], v[238:241], v[4:7]
	v_mfma_f32_16x16x32_bf16 v[0:3], v[190:193], v[238:241], v[0:3]
	s_barrier
	s_setprio 0
	s_add_i32 s53, s53, 2
	s_add_u32 s22, s22, 0x100
	s_addc_u32 s23, s23, 0
	s_add_u32 s47, s47, 0x100
	s_addc_u32 s51, s51, 0
	s_cmp_gt_u32 s53, 29
